# P2 prompt chunk loop: packed v_pk_mul_f32 split into scalar v_mul_f32 pairs (31 sites beside MFMAs)
# speedup vs baseline: 1.0647x; 1.0046x over previous
; #define LAS __attribute__((address_space(3)))
; __device__ __forceinline__ float bflo(unsigned w) { return __uint_as_float(w << 16); }
; __device__ __forceinline__ float bfhi(unsigned w) { return __uint_as_float(w & 0xffff0000u); }
; __device__ __forceinline__ unsigned pk2(float lo, float hi) { unsigned r; asm("v_cvt_pk_bf16_f32 %0, %1, %2" : "=v"(r) : "v"(lo), "v"(hi)); return r; }
; #define SSD_ISSUE_Z(cn) do { const bf16_t* q_ = PROJ + ((size_t)b * TP + (size_t)(cn) * 128 + trow) * NPROJ + C_Z + h * 64 + 4 * fq; \
;         _Pragma("unroll") for (int pt = 0; pt < 4; ++pt) rz[pt] = *(const u32x2*)(q_ + 16 * pt); } while (0)
; __device__ __forceinline__ void ssd_prompt(const Params& p, LAS unsigned char* lds, int b, int h) {
;     ...
;         SSD_ISSUE_Z(cn);
;         __syncthreads();
;         {
;             const float dec = __expf(sAc[127]);
;             const int ptile = wid & 3, nt0 = (wid >> 2) * 4;
; #pragma unroll
;             for (int i = 0; i < 4; ++i) hacc[i] *= dec;
; #pragma unroll
;             for (int kk = 0; kk < 4; ++kk) {
;                 const int sb = 32 * kk + 8 * fq;
;                 const u32x2 xlo = tr4(sX, XROW, sb, 16 * ptile, fr), xhi = tr4(sX, XROW, sb + 4, 16 * ptile, fr);
;                 const f32x4 w0 = *(const LAS f32x4*)(sW + sb), w1 = *(const LAS f32x4*)(sW + sb + 4);
;                 u32x2 blo[4], bhi[4];
; #pragma unroll
;                 for (int i = 0; i < 4; ++i) { blo[i] = tr4(sB, LROW, sb, 16 * (nt0 + i), fr); bhi[i] = tr4(sB, LROW, sb + 4, 16 * (nt0 + i), fr); }
;                 u32x4 w;
;                 w.x = pk2(bflo(xlo.x) * w0[0], bfhi(xlo.x) * w0[1]); w.y = pk2(bflo(xlo.y) * w0[2], bfhi(xlo.y) * w0[3]);
;                 w.z = pk2(bflo(xhi.x) * w1[0], bfhi(xhi.x) * w1[1]); w.w = pk2(bflo(xhi.y) * w1[2], bfhi(xhi.y) * w1[3]);
;                 const bf16x8 xa = __builtin_bit_cast(bf16x8, w);
; #pragma unroll
;                 for (int i = 0; i < 4; ++i) { u32x4 bw; bw.x = blo[i].x; bw.y = blo[i].y; bw.z = bhi[i].x; bw.w = bhi[i].y;
;                     hacc[i] = __builtin_amdgcn_mfma_f32_16x16x32_bf16(xa, __builtin_bit_cast(bf16x8, bw), hacc[i], 0, 0, 0); }
;             }
.LBB0_529:
	s_or_b64 exec, exec, s[2:3]
	s_waitcnt lgkmcnt(0)
	v_lshl_add_u64 v[56:57], s[10:11], 0, v[126:127]
	v_mad_u64_u32 v[58:59], s[2:3], v56, s83, v[130:131]
	v_mov_b32_e32 v56, v59
	v_mad_u64_u32 v[56:57], s[2:3], v57, s83, v[56:57]
	v_mov_b32_e32 v59, v56
	v_mov_b32_e32 v56, s97
	global_load_dwordx2 v[148:149], v[58:59], off
	global_load_dwordx2 v[146:147], v[58:59], off offset:32
	global_load_dwordx2 v[144:145], v[58:59], off offset:64
	global_load_dwordx2 v[140:141], v[58:59], off offset:96
	s_barrier
	ds_read_b32 v56, v56
	ds_read_b64_tr_b16 v[74:75], v190
	ds_read_b64_tr_b16 v[76:77], v190 offset:576
	s_cmpk_lg_i32 s90, 0x880
	s_mov_b32 s2, s90
	s_waitcnt lgkmcnt(2)
	v_mul_f32_e32 v56, 0x3fb8aa3b, v56
	v_exp_f32_e32 v72, v56
	ds_read_b128 v[56:59], v133
	ds_read_b128 v[60:63], v133 offset:16
	ds_read_b64_tr_b16 v[66:67], v170 offset:18464
	ds_read_b64_tr_b16 v[68:69], v169 offset:18432
	ds_read_b64_tr_b16 v[64:65], v169 offset:18464
	ds_read_b64_tr_b16 v[70:71], v170 offset:18432
	v_mul_f32_e32 v50, v50, v72
	v_mul_f32_e32 v51, v51, v72
	v_mul_f32_e32 v48, v48, v72
	v_mul_f32_e32 v49, v49, v72
	v_mul_f32_e32 v54, v54, v72
	v_mul_f32_e32 v55, v55, v72
	v_mul_f32_e32 v52, v52, v72
	v_mul_f32_e32 v53, v53, v72
	s_waitcnt lgkmcnt(7)
	v_lshlrev_b32_e32 v73, 16, v74
	s_waitcnt lgkmcnt(5)
	v_mul_f32_e32 v56, v56, v73
	v_and_b32_e32 v73, 0xffff0000, v74
	v_mul_f32_e32 v57, v57, v73
	v_cvt_pk_bf16_f32 v56, v56, v57
	v_lshlrev_b32_e32 v57, 16, v75
	v_mul_f32_e32 v57, v58, v57
	v_and_b32_e32 v58, 0xffff0000, v75
	v_mul_f32_e32 v58, v59, v58
	v_cvt_pk_bf16_f32 v57, v57, v58
	v_lshlrev_b32_e32 v58, 16, v76
	v_and_b32_e32 v59, 0xffff0000, v76
	s_waitcnt lgkmcnt(4)
	v_mul_f32_e32 v58, v60, v58
	v_mul_f32_e32 v59, v61, v59
	v_cvt_pk_bf16_f32 v58, v58, v59
	v_lshlrev_b32_e32 v59, 16, v77
	v_and_b32_e32 v60, 0xffff0000, v77
	v_mul_f32_e32 v59, v62, v59
	v_mul_f32_e32 v60, v63, v60
	v_cvt_pk_bf16_f32 v59, v59, v60
	v_mul_f32_e32 v46, v46, v72
	v_mul_f32_e32 v47, v47, v72
	s_waitcnt lgkmcnt(0)
	v_mfma_f32_16x16x32_bf16 v[48:51], v[56:59], v[68:71], v[48:51]
	ds_read_b64_tr_b16 v[60:61], v169 offset:18496
	ds_read_b64_tr_b16 v[62:63], v170 offset:18496
	ds_read_b64_tr_b16 v[68:69], v161 offset:18432
	ds_read_b64_tr_b16 v[70:71], v162 offset:18432
	ds_read_b64_tr_b16 v[74:75], v191
	v_mul_f32_e32 v44, v44, v72
	v_mul_f32_e32 v45, v45, v72
	v_mul_f32_e32 v42, v42, v72
	v_mul_f32_e32 v43, v43, v72
	v_mul_f32_e32 v40, v40, v72
	v_mul_f32_e32 v41, v41, v72
	v_mfma_f32_16x16x32_bf16 v[52:55], v[56:59], v[64:67], v[52:55]
	s_waitcnt lgkmcnt(0)
	v_lshlrev_b32_e32 v72, 16, v74
	v_mfma_f32_16x16x32_bf16 v[44:47], v[56:59], v[60:63], v[44:47]
	v_mfma_f32_16x16x32_bf16 v[40:43], v[56:59], v[68:71], v[40:43]
	ds_read_b64_tr_b16 v[70:71], v191 offset:576
	ds_read_b128 v[56:59], v135
	ds_read_b128 v[60:63], v135 offset:16
	ds_read_b64_tr_b16 v[64:65], v172 offset:18464
	ds_read_b64_tr_b16 v[66:67], v171 offset:18432
	ds_read_b64_tr_b16 v[68:69], v172 offset:18432
	s_waitcnt lgkmcnt(4)
	v_mul_f32_e32 v56, v56, v72
	v_and_b32_e32 v72, 0xffff0000, v74
	v_mul_f32_e32 v57, v57, v72
	v_cvt_pk_bf16_f32 v56, v56, v57
	v_lshlrev_b32_e32 v57, 16, v75
	v_mul_f32_e32 v57, v58, v57
	v_and_b32_e32 v58, 0xffff0000, v75
	v_mul_f32_e32 v58, v59, v58
	v_cvt_pk_bf16_f32 v57, v57, v58
	v_lshlrev_b32_e32 v58, 16, v70
	v_and_b32_e32 v59, 0xffff0000, v70
	s_waitcnt lgkmcnt(3)
	v_mul_f32_e32 v58, v60, v58
	v_mul_f32_e32 v59, v61, v59
	v_cvt_pk_bf16_f32 v58, v58, v59
	v_lshlrev_b32_e32 v59, 16, v71
	v_and_b32_e32 v60, 0xffff0000, v71
	v_mul_f32_e32 v59, v62, v59
	v_mul_f32_e32 v60, v63, v60
	v_cvt_pk_bf16_f32 v59, v59, v60
	ds_read_b64_tr_b16 v[62:63], v171 offset:18464
	ds_read_b64_tr_b16 v[60:61], v171 offset:18496
	s_waitcnt lgkmcnt(1)
	v_mfma_f32_16x16x32_bf16 v[52:55], v[56:59], v[62:65], v[52:55]
	ds_read_b64_tr_b16 v[62:63], v172 offset:18496
	ds_read_b64_tr_b16 v[64:65], v163 offset:18432
	v_mfma_f32_16x16x32_bf16 v[48:51], v[56:59], v[66:69], v[48:51]
	ds_read_b64_tr_b16 v[66:67], v164 offset:18432
	ds_read_b64_tr_b16 v[70:71], v193
	ds_read_b64_tr_b16 v[72:73], v193 offset:576
	s_waitcnt lgkmcnt(1)
; #define LAS __attribute__((address_space(3)))
; __device__ __forceinline__ float bflo(unsigned w) { return __uint_as_float(w << 16); }
; __device__ __forceinline__ float bfhi(unsigned w) { return __uint_as_float(w & 0xffff0000u); }
; __device__ __forceinline__ unsigned pk2(float lo, float hi) { unsigned r; asm("v_cvt_pk_bf16_f32 %0, %1, %2" : "=v"(r) : "v"(lo), "v"(hi)); return r; }
; __device__ __forceinline__ bf16_t f2bf(float f) { return (bf16_t)(pk2(f, 0.f) & 0xffffu); }
; __device__ __forceinline__ void ssd_prompt(const Params& p, LAS unsigned char* lds, int b, int h) {
;     ...
;             for (int kk = 0; kk < 4; ++kk) {
;                 const int sb = 32 * kk + 8 * fq;
;                 const u32x2 xlo = tr4(sX, XROW, sb, 16 * ptile, fr), xhi = tr4(sX, XROW, sb + 4, 16 * ptile, fr);
;                 const f32x4 w0 = *(const LAS f32x4*)(sW + sb), w1 = *(const LAS f32x4*)(sW + sb + 4);
;                 u32x2 blo[4], bhi[4];
; #pragma unroll
;                 for (int i = 0; i < 4; ++i) { blo[i] = tr4(sB, LROW, sb, 16 * (nt0 + i), fr); bhi[i] = tr4(sB, LROW, sb + 4, 16 * (nt0 + i), fr); }
;                 u32x4 w;
;                 w.x = pk2(bflo(xlo.x) * w0[0], bfhi(xlo.x) * w0[1]); w.y = pk2(bflo(xlo.y) * w0[2], bfhi(xlo.y) * w0[3]);
;                 w.z = pk2(bflo(xhi.x) * w1[0], bfhi(xhi.x) * w1[1]); w.w = pk2(bflo(xhi.y) * w1[2], bfhi(xhi.y) * w1[3]);
;                 const bf16x8 xa = __builtin_bit_cast(bf16x8, w);
; #pragma unroll
;                 for (int i = 0; i < 4; ++i) { u32x4 bw; bw.x = blo[i].x; bw.y = blo[i].y; bw.z = bhi[i].x; bw.w = bhi[i].y;
;                     hacc[i] = __builtin_amdgcn_mfma_f32_16x16x32_bf16(xa, __builtin_bit_cast(bf16x8, bw), hacc[i], 0, 0, 0); }
;             }
; #pragma unroll
;             for (int i = 0; i < 4; ++i)
; #pragma unroll
;                 for (int jj = 0; jj < 4; ++jj) sH[(16 * ptile + 4 * fq + jj) * LROW + 16 * (nt0 + i) + fr] = f2bf(hacc[i][jj]);
;         }
;         __syncthreads();
	v_lshlrev_b32_e32 v74, 16, v70
	v_mfma_f32_16x16x32_bf16 v[44:47], v[56:59], v[60:63], v[44:47]
	v_and_b32_e32 v70, 0xffff0000, v70
	v_mfma_f32_16x16x32_bf16 v[40:43], v[56:59], v[64:67], v[40:43]
	ds_read_b128 v[56:59], v137
	ds_read_b128 v[60:63], v137 offset:16
	ds_read_b64_tr_b16 v[64:65], v174 offset:18464
	ds_read_b64_tr_b16 v[66:67], v173 offset:18432
	ds_read_b64_tr_b16 v[68:69], v174 offset:18432
	s_waitcnt lgkmcnt(4)
	v_mul_f32_e32 v56, v56, v74
	v_mul_f32_e32 v57, v57, v70
	v_cvt_pk_bf16_f32 v56, v56, v57
	v_lshlrev_b32_e32 v57, 16, v71
	v_mul_f32_e32 v57, v58, v57
	v_and_b32_e32 v58, 0xffff0000, v71
	v_mul_f32_e32 v58, v59, v58
	v_cvt_pk_bf16_f32 v57, v57, v58
	v_lshlrev_b32_e32 v58, 16, v72
	v_and_b32_e32 v59, 0xffff0000, v72
	s_waitcnt lgkmcnt(3)
	v_mul_f32_e32 v58, v60, v58
	v_mul_f32_e32 v59, v61, v59
	v_cvt_pk_bf16_f32 v58, v58, v59
	v_lshlrev_b32_e32 v59, 16, v73
	v_and_b32_e32 v60, 0xffff0000, v73
	v_mul_f32_e32 v59, v62, v59
	v_mul_f32_e32 v60, v63, v60
	v_cvt_pk_bf16_f32 v59, v59, v60
	ds_read_b64_tr_b16 v[62:63], v173 offset:18464
	ds_read_b64_tr_b16 v[60:61], v173 offset:18496
	s_waitcnt lgkmcnt(2)
	v_mfma_f32_16x16x32_bf16 v[48:51], v[56:59], v[66:69], v[48:51]
	s_waitcnt lgkmcnt(1)
	v_mfma_f32_16x16x32_bf16 v[52:55], v[56:59], v[62:65], v[52:55]
	ds_read_b64_tr_b16 v[62:63], v174 offset:18496
	ds_read_b64_tr_b16 v[64:65], v165 offset:18432
	ds_read_b64_tr_b16 v[66:67], v166 offset:18432
	ds_read_b64_tr_b16 v[70:71], v194
	s_waitcnt lgkmcnt(0)
	v_lshlrev_b32_e32 v74, 16, v70
	v_mfma_f32_16x16x32_bf16 v[44:47], v[56:59], v[60:63], v[44:47]
	v_and_b32_e32 v70, 0xffff0000, v70
	v_mfma_f32_16x16x32_bf16 v[40:43], v[56:59], v[64:67], v[40:43]
	ds_read_b64_tr_b16 v[72:73], v194 offset:576
	ds_read_b128 v[56:59], v139
	ds_read_b128 v[60:63], v139 offset:16
	ds_read_b64_tr_b16 v[64:65], v176 offset:18464
	ds_read_b64_tr_b16 v[66:67], v175 offset:18432
	ds_read_b64_tr_b16 v[68:69], v176 offset:18432
	s_waitcnt lgkmcnt(4)
	v_mul_f32_e32 v56, v56, v74
	v_mul_f32_e32 v57, v57, v70
	v_cvt_pk_bf16_f32 v56, v56, v57
	v_lshlrev_b32_e32 v57, 16, v71
	v_mul_f32_e32 v57, v58, v57
	v_and_b32_e32 v58, 0xffff0000, v71
	v_mul_f32_e32 v58, v59, v58
	v_cvt_pk_bf16_f32 v57, v57, v58
	v_lshlrev_b32_e32 v58, 16, v72
	v_and_b32_e32 v59, 0xffff0000, v72
	s_waitcnt lgkmcnt(3)
	v_mul_f32_e32 v58, v60, v58
	v_mul_f32_e32 v59, v61, v59
	v_cvt_pk_bf16_f32 v58, v58, v59
	v_lshlrev_b32_e32 v59, 16, v73
	v_and_b32_e32 v60, 0xffff0000, v73
	v_mul_f32_e32 v59, v62, v59
	v_mul_f32_e32 v60, v63, v60
	v_cvt_pk_bf16_f32 v59, v59, v60
	ds_read_b64_tr_b16 v[62:63], v175 offset:18464
	ds_read_b64_tr_b16 v[60:61], v175 offset:18496
	s_waitcnt lgkmcnt(2)
	v_mfma_f32_16x16x32_bf16 v[48:51], v[56:59], v[66:69], v[48:51]
	s_waitcnt lgkmcnt(1)
	v_mfma_f32_16x16x32_bf16 v[52:55], v[56:59], v[62:65], v[52:55]
	ds_read_b64_tr_b16 v[62:63], v176 offset:18496
	ds_read_b64_tr_b16 v[64:65], v167 offset:18432
	ds_read_b64_tr_b16 v[66:67], v168 offset:18432
	s_waitcnt lgkmcnt(2)
	v_mfma_f32_16x16x32_bf16 v[44:47], v[56:59], v[60:63], v[44:47]
	s_waitcnt lgkmcnt(0)
	v_mfma_f32_16x16x32_bf16 v[40:43], v[56:59], v[64:67], v[40:43]
	v_cvt_pk_bf16_f32 v56, v48, v109
	ds_write_b16 v195, v56
	v_cvt_pk_bf16_f32 v56, v49, v109
	ds_write_b16 v195, v56 offset:272
	v_cvt_pk_bf16_f32 v56, v50, v109
	ds_write_b16 v195, v56 offset:544
	v_cvt_pk_bf16_f32 v56, v51, v109
	ds_write_b16 v195, v56 offset:816
	v_cvt_pk_bf16_f32 v56, v52, v109
	ds_write_b16 v196, v56
	v_cvt_pk_bf16_f32 v56, v53, v109
	ds_write_b16 v196, v56 offset:272
	v_cvt_pk_bf16_f32 v56, v54, v109
	ds_write_b16 v196, v56 offset:544
	v_cvt_pk_bf16_f32 v56, v55, v109
	ds_write_b16 v196, v56 offset:816
	v_cvt_pk_bf16_f32 v56, v44, v109
	ds_write_b16 v197, v56
	v_cvt_pk_bf16_f32 v56, v45, v109
	ds_write_b16 v197, v56 offset:272
	v_cvt_pk_bf16_f32 v56, v46, v109
	ds_write_b16 v197, v56 offset:544
	v_cvt_pk_bf16_f32 v56, v47, v109
	ds_write_b16 v197, v56 offset:816
	v_cvt_pk_bf16_f32 v56, v40, v109
	ds_write_b16 v198, v56
	v_cvt_pk_bf16_f32 v56, v41, v109
	ds_write_b16 v198, v56 offset:272
	v_cvt_pk_bf16_f32 v56, v42, v109
	ds_write_b16 v198, v56 offset:544
	v_cvt_pk_bf16_f32 v56, v43, v109
	ds_write_b16 v198, v56 offset:816
	s_waitcnt lgkmcnt(0)
	s_barrier
	s_cbranch_scc0 .LBB0_538

; #define LAS __attribute__((address_space(3)))
; __device__ __forceinline__ unsigned pk2(float lo, float hi) { unsigned r; asm("v_cvt_pk_bf16_f32 %0, %1, %2" : "=v"(r) : "v"(lo), "v"(hi)); return r; }
; __device__ __forceinline__ void ssd_prompt(const Params& p, LAS unsigned char* lds, int b, int h) {
;     ...
;         const float act = sAc[trow];
;         bf16x8 cf[4];
; #pragma unroll
;         for (int kk = 0; kk < 4; ++kk) cf[kk] = *(const LAS bf16x8*)(sC + trow * LROW + 32 * kk + 8 * fq);
;         f32x4 d[8];
; #pragma unroll
;         for (int st = 0; st < 8; ++st) d[st] = (f32x4){0.f, 0.f, 0.f, 0.f};
; #pragma unroll
;         for (int kk = 0; kk < 4; ++kk) {
;             bf16x8 bfr[8];
; #pragma unroll
;             for (int st = 0; st < 8; ++st) bfr[st] = *(const LAS bf16x8*)(sB + (16 * st + fr) * LROW + 32 * kk + 8 * fq);
; #pragma unroll
;             for (int st = 0; st < 8; ++st) d[st] = __builtin_amdgcn_mfma_f32_16x16x32_bf16(bfr[st], cf[kk], d[st], 0, 0, 0);
;         }
;         bf16x8 gfrag[4];
;         {
; #pragma unroll
;             for (int kb = 0; kb < 4; ++kb) {
;                 f32x4 acs[2], dts[2];
; #pragma unroll
;                 for (int hf = 0; hf < 2; ++hf) { acs[hf] = *(const LAS f32x4*)(sAc + 16 * (2 * kb + hf) + 4 * fq); dts[hf] = *(const LAS f32x4*)(sDt + 16 * (2 * kb + hf) + 4 * fq); }
;                 unsigned pkd[4];
; #pragma unroll
;                 for (int hf = 0; hf < 2; ++hf) { const int st = 2 * kb + hf; float gv[4];
; #pragma unroll
;                     for (int jj = 0; jj < 4; ++jj) { const int s = 16 * st + 4 * fq + jj; gv[jj] = (s <= trow) ? d[st][jj] * __expf(act - acs[hf][jj]) * dts[hf][jj] : 0.f; }
;                     pkd[2 * hf] = pk2(gv[0], gv[1]); pkd[2 * hf + 1] = pk2(gv[2], gv[3]); }
;                 u32x4 w; w.x = pkd[0]; w.y = pkd[1]; w.z = pkd[2]; w.w = pkd[3];
;                 gfrag[kb] = __builtin_bit_cast(bf16x8, w);
;             }
.LBB0_536:
	s_or_b64 exec, exec, s[74:75]
	ds_read_b32 v106, v152
	ds_read_b128 v[80:83], v180 offset:53248
	ds_read_b128 v[76:79], v180 offset:53312
	ds_read_b128 v[72:75], v180 offset:53376
	ds_read_b128 v[56:59], v180 offset:53440
	ds_read_b128 v[60:63], v181 offset:18432
	ds_read_b128 v[64:67], v181 offset:22784
	ds_read_b128 v[68:71], v181 offset:27136
	ds_read_b128 v[84:87], v181 offset:31488
	ds_read_b128 v[88:91], v181 offset:35840
	ds_read_b128 v[92:95], v181 offset:40192
	ds_read_b128 v[96:99], v181 offset:44544
	ds_read_b128 v[100:103], v181 offset:48896
	ds_read_b128 v[200:203], v181 offset:18496
	ds_read_b128 v[204:207], v181 offset:22848
	ds_read_b128 v[208:211], v181 offset:27200
	ds_read_b128 v[212:215], v181 offset:31552
	ds_read_b128 v[216:219], v181 offset:35904
	ds_read_b128 v[220:223], v181 offset:40256
	ds_read_b128 v[224:227], v181 offset:44608
	ds_read_b128 v[228:231], v181 offset:48960
	s_waitcnt lgkmcnt(14)
	v_mfma_f32_16x16x32_bf16 v[60:63], v[60:63], v[80:83], 0
	v_readlane_b32 s74, v243, 1
	v_readlane_b32 s75, v243, 2
	v_mfma_f32_16x16x32_bf16 v[64:67], v[64:67], v[80:83], 0
	s_waitcnt lgkmcnt(13)
	v_mfma_f32_16x16x32_bf16 v[68:71], v[68:71], v[80:83], 0
	s_waitcnt lgkmcnt(12)
	v_mfma_f32_16x16x32_bf16 v[84:87], v[84:87], v[80:83], 0
	s_waitcnt lgkmcnt(11)
	v_mfma_f32_16x16x32_bf16 v[88:91], v[88:91], v[80:83], 0
	s_waitcnt lgkmcnt(10)
	v_mfma_f32_16x16x32_bf16 v[92:95], v[92:95], v[80:83], 0
	s_waitcnt lgkmcnt(9)
	v_mfma_f32_16x16x32_bf16 v[96:99], v[96:99], v[80:83], 0
	s_waitcnt lgkmcnt(8)
	v_mfma_f32_16x16x32_bf16 v[100:103], v[100:103], v[80:83], 0
	s_waitcnt lgkmcnt(7)
	v_mfma_f32_16x16x32_bf16 v[60:63], v[200:203], v[76:79], v[60:63]
	s_waitcnt lgkmcnt(6)
	v_mfma_f32_16x16x32_bf16 v[64:67], v[204:207], v[76:79], v[64:67]
	s_waitcnt lgkmcnt(5)
	v_mfma_f32_16x16x32_bf16 v[68:71], v[208:211], v[76:79], v[68:71]
	s_waitcnt lgkmcnt(4)
	v_mfma_f32_16x16x32_bf16 v[84:87], v[212:215], v[76:79], v[84:87]
	s_waitcnt lgkmcnt(3)
	v_mfma_f32_16x16x32_bf16 v[88:91], v[216:219], v[76:79], v[88:91]
	s_waitcnt lgkmcnt(2)
	v_mfma_f32_16x16x32_bf16 v[92:95], v[220:223], v[76:79], v[92:95]
	s_waitcnt lgkmcnt(1)
	v_mfma_f32_16x16x32_bf16 v[96:99], v[224:227], v[76:79], v[96:99]
	s_waitcnt lgkmcnt(0)
	v_mfma_f32_16x16x32_bf16 v[100:103], v[228:231], v[76:79], v[100:103]
	ds_read_b128 v[200:203], v181 offset:18560
	ds_read_b128 v[204:207], v181 offset:22912
	ds_read_b128 v[208:211], v181 offset:27264
	ds_read_b128 v[212:215], v181 offset:31616
	ds_read_b128 v[216:219], v181 offset:35968
	ds_read_b128 v[220:223], v181 offset:40320
	ds_read_b128 v[224:227], v181 offset:44672
	ds_read_b128 v[228:231], v181 offset:49024
	s_waitcnt lgkmcnt(7)
	v_mfma_f32_16x16x32_bf16 v[60:63], v[200:203], v[72:75], v[60:63]
	s_waitcnt lgkmcnt(6)
	v_mfma_f32_16x16x32_bf16 v[64:67], v[204:207], v[72:75], v[64:67]
	s_waitcnt lgkmcnt(5)
	v_mfma_f32_16x16x32_bf16 v[68:71], v[208:211], v[72:75], v[68:71]
	s_waitcnt lgkmcnt(4)
	v_mfma_f32_16x16x32_bf16 v[84:87], v[212:215], v[72:75], v[84:87]
	s_waitcnt lgkmcnt(3)
	v_mfma_f32_16x16x32_bf16 v[88:91], v[216:219], v[72:75], v[88:91]
	s_waitcnt lgkmcnt(2)
	v_mfma_f32_16x16x32_bf16 v[92:95], v[220:223], v[72:75], v[92:95]
	s_waitcnt lgkmcnt(1)
	v_mfma_f32_16x16x32_bf16 v[96:99], v[224:227], v[72:75], v[96:99]
	s_waitcnt lgkmcnt(0)
	v_mfma_f32_16x16x32_bf16 v[100:103], v[228:231], v[72:75], v[100:103]
	ds_read_b128 v[200:203], v181 offset:18624
	ds_read_b128 v[204:207], v181 offset:22976
	ds_read_b128 v[208:211], v181 offset:27328
	ds_read_b128 v[212:215], v181 offset:31680
	ds_read_b128 v[216:219], v181 offset:36032
	ds_read_b128 v[220:223], v181 offset:40384
	ds_read_b128 v[224:227], v181 offset:44736
	ds_read_b128 v[228:231], v181 offset:49088
	s_waitcnt lgkmcnt(7)
	v_mfma_f32_16x16x32_bf16 v[60:63], v[200:203], v[56:59], v[60:63]
	s_waitcnt lgkmcnt(6)
	v_mfma_f32_16x16x32_bf16 v[64:67], v[204:207], v[56:59], v[64:67]
	s_waitcnt lgkmcnt(5)
	v_mfma_f32_16x16x32_bf16 v[200:203], v[208:211], v[56:59], v[68:71]
	s_waitcnt lgkmcnt(4)
	v_mfma_f32_16x16x32_bf16 v[204:207], v[212:215], v[56:59], v[84:87]
	s_waitcnt lgkmcnt(3)
	v_mfma_f32_16x16x32_bf16 v[208:211], v[216:219], v[56:59], v[88:91]
	s_waitcnt lgkmcnt(2)
	v_mfma_f32_16x16x32_bf16 v[212:215], v[220:223], v[56:59], v[92:95]
	s_waitcnt lgkmcnt(1)
	v_mfma_f32_16x16x32_bf16 v[90:93], v[224:227], v[56:59], v[96:99]
	s_waitcnt lgkmcnt(0)
	v_mfma_f32_16x16x32_bf16 v[86:89], v[228:231], v[56:59], v[100:103]
	ds_read_b128 v[68:71], v153
	ds_read_b128 v[94:97], v154
	s_nop 0
	ds_read_b128 v[98:101], v153 offset:64
	ds_read_b128 v[102:105], v154 offset:64
	s_waitcnt lgkmcnt(3)
	v_sub_f32_e32 v68, v106, v68
	v_mul_f32_e32 v68, 0x3fb8aa3b, v68
	v_exp_f32_e32 v68, v68
	s_nop 0
	v_mul_f32_e32 v60, v60, v68
	v_sub_f32_e32 v68, v106, v69
	v_mul_f32_e32 v68, 0x3fb8aa3b, v68
	v_exp_f32_e32 v68, v68
	s_waitcnt lgkmcnt(2)
	v_mul_f32_e32 v60, v94, v60
	v_cndmask_b32_e64 v60, v60, 0, s[74:75]
	v_readlane_b32 s74, v243, 3
	v_mul_f32_e32 v61, v61, v68
	v_sub_f32_e32 v68, v106, v70
	v_mul_f32_e32 v68, 0x3fb8aa3b, v68
	v_exp_f32_e32 v68, v68
	v_mul_f32_e32 v61, v95, v61
	v_readlane_b32 s75, v243, 4
	v_mul_f32_e32 v62, v62, v68
	v_sub_f32_e32 v68, v106, v71
	v_mul_f32_e32 v68, 0x3fb8aa3b, v68
	v_exp_f32_e32 v68, v68
	v_mul_f32_e32 v62, v96, v62
	v_cndmask_b32_e64 v61, 0, v61, s[74:75]
	v_cndmask_b32_e64 v62, v62, 0, s[12:13]
	v_mul_f32_e32 v63, v63, v68
	v_mul_f32_e32 v63, v97, v63
	v_cndmask_b32_e64 v63, v63, 0, s[14:15]
	v_cvt_pk_bf16_f32 v68, v60, v61
	v_cvt_pk_bf16_f32 v69, v62, v63
	s_waitcnt lgkmcnt(1)
; #define LAS __attribute__((address_space(3)))
; __device__ __forceinline__ unsigned pk2(float lo, float hi) { unsigned r; asm("v_cvt_pk_bf16_f32 %0, %1, %2" : "=v"(r) : "v"(lo), "v"(hi)); return r; }
; __device__ __forceinline__ void ssd_prompt(const Params& p, LAS unsigned char* lds, int b, int h) {
;     ...
;             for (int kb = 0; kb < 4; ++kb) {
;                 f32x4 acs[2], dts[2];
; #pragma unroll
;                 for (int hf = 0; hf < 2; ++hf) { acs[hf] = *(const LAS f32x4*)(sAc + 16 * (2 * kb + hf) + 4 * fq); dts[hf] = *(const LAS f32x4*)(sDt + 16 * (2 * kb + hf) + 4 * fq); }
;                 unsigned pkd[4];
; #pragma unroll
;                 for (int hf = 0; hf < 2; ++hf) { const int st = 2 * kb + hf; float gv[4];
; #pragma unroll
;                     for (int jj = 0; jj < 4; ++jj) { const int s = 16 * st + 4 * fq + jj; gv[jj] = (s <= trow) ? d[st][jj] * __expf(act - acs[hf][jj]) * dts[hf][jj] : 0.f; }
;                     pkd[2 * hf] = pk2(gv[0], gv[1]); pkd[2 * hf + 1] = pk2(gv[2], gv[3]); }
;                 u32x4 w; w.x = pkd[0]; w.y = pkd[1]; w.z = pkd[2]; w.w = pkd[3];
;                 gfrag[kb] = __builtin_bit_cast(bf16x8, w);
;             }
	v_sub_f32_e32 v60, v106, v98
	v_sub_f32_e32 v61, v106, v99
	v_sub_f32_e32 v62, v106, v100
	v_sub_f32_e32 v63, v106, v101
	v_mul_f32_e32 v60, 0x3fb8aa3b, v60
	v_mul_f32_e32 v61, 0x3fb8aa3b, v61
	v_mul_f32_e32 v62, 0x3fb8aa3b, v62
	v_mul_f32_e32 v63, 0x3fb8aa3b, v63
	v_exp_f32_e32 v60, v60
	v_exp_f32_e32 v61, v61
	v_exp_f32_e32 v62, v62
	v_exp_f32_e32 v63, v63
	v_mul_f32_e32 v60, v64, v60
	v_mul_f32_e32 v61, v65, v61
	v_mul_f32_e32 v62, v66, v62
	v_mul_f32_e32 v63, v67, v63
	s_waitcnt lgkmcnt(0)
	v_mul_f32_e32 v60, v102, v60
	v_mul_f32_e32 v61, v103, v61
	v_mul_f32_e32 v62, v104, v62
	v_mul_f32_e32 v63, v105, v63
	v_cndmask_b32_e64 v60, v60, 0, s[0:1]
	v_cndmask_b32_e64 v61, v61, 0, s[84:85]
	v_cndmask_b32_e64 v62, v62, 0, s[86:87]
	v_cndmask_b32_e64 v63, v63, 0, s[88:89]
	v_cvt_pk_bf16_f32 v70, v60, v61
	v_cvt_pk_bf16_f32 v71, v62, v63
	ds_read_b128 v[60:63], v153 offset:128
	ds_read_b128 v[64:67], v154 offset:128
	ds_read_b128 v[94:97], v153 offset:192
	ds_read_b128 v[98:101], v154 offset:192
	s_waitcnt lgkmcnt(3)
	v_sub_f32_e32 v60, v106, v60
	v_sub_f32_e32 v61, v106, v61
	v_sub_f32_e32 v62, v106, v62
	v_sub_f32_e32 v63, v106, v63
	v_mul_f32_e32 v60, 0x3fb8aa3b, v60
	v_mul_f32_e32 v61, 0x3fb8aa3b, v61
	v_mul_f32_e32 v62, 0x3fb8aa3b, v62
	v_mul_f32_e32 v63, 0x3fb8aa3b, v63
	v_exp_f32_e32 v60, v60
	v_exp_f32_e32 v61, v61
	v_exp_f32_e32 v62, v62
	v_exp_f32_e32 v63, v63
	v_mul_f32_e32 v60, v200, v60
	v_mul_f32_e32 v61, v201, v61
	v_mul_f32_e32 v62, v202, v62
	v_mul_f32_e32 v63, v203, v63
	s_waitcnt lgkmcnt(2)
	v_mul_f32_e32 v60, v64, v60
	v_mul_f32_e32 v61, v65, v61
	v_mul_f32_e32 v62, v66, v62
	v_mul_f32_e32 v63, v67, v63
	v_cndmask_b32_e64 v60, v60, 0, s[24:25]
	v_cndmask_b32_e64 v61, v61, 0, s[26:27]
	v_cndmask_b32_e64 v62, v62, 0, s[28:29]
	v_cndmask_b32_e64 v63, v63, 0, s[30:31]
	v_cvt_pk_bf16_f32 v64, v60, v61
	v_cvt_pk_bf16_f32 v65, v62, v63
	s_waitcnt lgkmcnt(1)
	v_sub_f32_e32 v60, v106, v94
	v_sub_f32_e32 v61, v106, v95
	v_sub_f32_e32 v62, v106, v96
	v_sub_f32_e32 v63, v106, v97
	v_mul_f32_e32 v60, 0x3fb8aa3b, v60
	v_mul_f32_e32 v61, 0x3fb8aa3b, v61
	v_mul_f32_e32 v62, 0x3fb8aa3b, v62
	v_mul_f32_e32 v63, 0x3fb8aa3b, v63
	v_exp_f32_e32 v60, v60
	v_exp_f32_e32 v61, v61
	v_exp_f32_e32 v62, v62
	v_exp_f32_e32 v63, v63
	v_mul_f32_e32 v60, v204, v60
	v_mul_f32_e32 v61, v205, v61
	v_mul_f32_e32 v62, v206, v62
	v_mul_f32_e32 v63, v207, v63
	s_waitcnt lgkmcnt(0)
	v_mul_f32_e32 v60, v98, v60
	v_mul_f32_e32 v61, v99, v61
	v_mul_f32_e32 v62, v100, v62
	v_mul_f32_e32 v63, v101, v63
	v_cndmask_b32_e64 v60, v60, 0, s[34:35]
	v_cndmask_b32_e64 v61, v61, 0, s[36:37]
	v_cndmask_b32_e64 v62, v62, 0, s[38:39]
	v_cndmask_b32_e64 v63, v63, 0, s[40:41]
	v_cvt_pk_bf16_f32 v66, v60, v61
	v_cvt_pk_bf16_f32 v67, v62, v63
	ds_read_b128 v[60:63], v153 offset:256
	ds_read_b128 v[94:97], v154 offset:256
	ds_read_b128 v[98:101], v153 offset:320
	ds_read_b128 v[102:105], v154 offset:320
	s_waitcnt lgkmcnt(3)
	v_sub_f32_e32 v60, v106, v60
	v_sub_f32_e32 v61, v106, v61
	v_sub_f32_e32 v62, v106, v62
	v_sub_f32_e32 v63, v106, v63
	v_mul_f32_e32 v60, 0x3fb8aa3b, v60
	v_mul_f32_e32 v61, 0x3fb8aa3b, v61
	v_mul_f32_e32 v62, 0x3fb8aa3b, v62
	v_mul_f32_e32 v63, 0x3fb8aa3b, v63
	v_exp_f32_e32 v60, v60
	v_exp_f32_e32 v61, v61
	v_exp_f32_e32 v62, v62
	v_exp_f32_e32 v63, v63
	v_mul_f32_e32 v60, v208, v60
	v_mul_f32_e32 v61, v209, v61
	v_mul_f32_e32 v62, v210, v62
	v_mul_f32_e32 v63, v211, v63
	s_waitcnt lgkmcnt(2)
	v_mul_f32_e32 v60, v94, v60
	v_mul_f32_e32 v61, v95, v61
	v_mul_f32_e32 v62, v96, v62
	v_mul_f32_e32 v63, v97, v63
	v_cndmask_b32_e64 v60, v60, 0, s[42:43]
	v_cndmask_b32_e64 v61, v61, 0, s[44:45]
	v_cndmask_b32_e64 v62, v62, 0, s[46:47]
	v_cndmask_b32_e64 v63, v63, 0, s[48:49]
	v_cvt_pk_bf16_f32 v60, v60, v61
	v_cvt_pk_bf16_f32 v61, v62, v63
	s_waitcnt lgkmcnt(1)
	v_sub_f32_e32 v62, v106, v98
	v_sub_f32_e32 v63, v106, v99
	v_sub_f32_e32 v84, v106, v100
	v_sub_f32_e32 v85, v106, v101
	v_mul_f32_e32 v62, 0x3fb8aa3b, v62
	v_mul_f32_e32 v63, 0x3fb8aa3b, v63
	v_mul_f32_e32 v84, 0x3fb8aa3b, v84
	v_mul_f32_e32 v85, 0x3fb8aa3b, v85
	v_exp_f32_e32 v62, v62
	v_exp_f32_e32 v63, v63
	v_exp_f32_e32 v84, v84
	v_exp_f32_e32 v85, v85
	v_mul_f32_e32 v62, v212, v62
	v_mul_f32_e32 v63, v213, v63
	v_mul_f32_e32 v84, v214, v84
	v_mul_f32_e32 v85, v215, v85
	s_waitcnt lgkmcnt(0)
	v_mul_f32_e32 v62, v102, v62
	v_mul_f32_e32 v63, v103, v63
	v_mul_f32_e32 v84, v104, v84
	v_mul_f32_e32 v85, v105, v85
	ds_read_b128 v[102:105], v153 offset:384
	ds_read_b128 v[98:101], v154 offset:384
	ds_read_b128 v[94:97], v153 offset:448
	ds_read_b128 v[200:203], v154 offset:448
	v_cndmask_b32_e64 v62, v62, 0, s[50:51]
	v_cndmask_b32_e64 v63, v63, 0, s[52:53]
	v_cndmask_b32_e64 v84, v84, 0, s[54:55]
	v_cndmask_b32_e64 v85, v85, 0, s[56:57]
	v_cvt_pk_bf16_f32 v62, v62, v63
	v_cvt_pk_bf16_f32 v63, v84, v85
	s_waitcnt lgkmcnt(3)
	v_sub_f32_e32 v84, v106, v102
	v_mul_f32_e32 v84, 0x3fb8aa3b, v84
	v_sub_f32_e32 v85, v106, v103
	v_exp_f32_e32 v84, v84
	v_mul_f32_e32 v85, 0x3fb8aa3b, v85
	v_exp_f32_e32 v85, v85
	v_mul_f32_e32 v84, v90, v84
	v_sub_f32_e32 v90, v106, v104
	v_mul_f32_e32 v85, v91, v85
	v_mul_f32_e32 v90, 0x3fb8aa3b, v90
	v_sub_f32_e32 v91, v106, v105
	v_exp_f32_e32 v90, v90
	v_mul_f32_e32 v91, 0x3fb8aa3b, v91
	v_exp_f32_e32 v91, v91
	s_waitcnt lgkmcnt(2)
	v_mul_f32_e32 v84, v98, v84
	v_mul_f32_e32 v90, v92, v90
	v_mul_f32_e32 v85, v99, v85
	v_mul_f32_e32 v90, v100, v90
	v_mul_f32_e32 v91, v93, v91
	v_cndmask_b32_e64 v84, v84, 0, s[58:59]
	v_cndmask_b32_e64 v85, v85, 0, s[60:61]
	v_cndmask_b32_e64 v90, v90, 0, s[62:63]
	v_mul_f32_e32 v91, v101, v91
	v_cndmask_b32_e64 v91, v91, 0, s[64:65]
	v_cvt_pk_bf16_f32 v84, v84, v85
	v_cvt_pk_bf16_f32 v85, v90, v91
	s_waitcnt lgkmcnt(1)
; #define LAS __attribute__((address_space(3)))
; __device__ __forceinline__ unsigned pk2(float lo, float hi) { unsigned r; asm("v_cvt_pk_bf16_f32 %0, %1, %2" : "=v"(r) : "v"(lo), "v"(hi)); return r; }
; __device__ __forceinline__ void ssd_prompt(const Params& p, LAS unsigned char* lds, int b, int h) {
;     ...
;                     for (int jj = 0; jj < 4; ++jj) { const int s = 16 * st + 4 * fq + jj; gv[jj] = (s <= trow) ? d[st][jj] * __expf(act - acs[hf][jj]) * dts[hf][jj] : 0.f; }
;                     pkd[2 * hf] = pk2(gv[0], gv[1]); pkd[2 * hf + 1] = pk2(gv[2], gv[3]); }
;                 u32x4 w; w.x = pkd[0]; w.y = pkd[1]; w.z = pkd[2]; w.w = pkd[3];
;                 gfrag[kb] = __builtin_bit_cast(bf16x8, w);
;             }
;         }
;         const float eact = __expf(act);
;         const int grow = base + trow;
;         f32x4 y[4];
; #pragma unroll
;         for (int pt = 0; pt < 4; ++pt) y[pt] = (f32x4){0.f, 0.f, 0.f, 0.f};
; #pragma unroll
;         for (int kk = 0; kk < 4; ++kk) {
;             bf16x8 hf[4];
; #pragma unroll
;             for (int pt = 0; pt < 4; ++pt) hf[pt] = *(const LAS bf16x8*)(sH + (16 * pt + fr) * LROW + 32 * kk + 8 * fq);
; #pragma unroll
;             for (int pt = 0; pt < 4; ++pt) y[pt] = __builtin_amdgcn_mfma_f32_16x16x32_bf16(hf[pt], cf[kk], y[pt], 0, 0, 0);
;         }
; #pragma unroll
;         for (int pt = 0; pt < 4; ++pt) y[pt] *= eact;
; #pragma unroll
;         for (int kb = 0; kb < 4; ++kb) {
;             u32x2 x0[4], x1[4];
; #pragma unroll
;             for (int pt = 0; pt < 4; ++pt) { x0[pt] = tr4(sX, XROW, 32 * kb + 4 * fq, 16 * pt, fr); x1[pt] = tr4(sX, XROW, 32 * kb + 16 + 4 * fq, 16 * pt, fr); }
; #pragma unroll
;             for (int pt = 0; pt < 4; ++pt) { u32x4 w; w.x = x0[pt].x; w.y = x0[pt].y; w.z = x1[pt].x; w.w = x1[pt].y;
;                 y[pt] = __builtin_amdgcn_mfma_f32_16x16x32_bf16(__builtin_bit_cast(bf16x8, w), gfrag[kb], y[pt], 0, 0, 0); }
	v_sub_f32_e32 v90, v106, v94
	v_mul_f32_e32 v90, 0x3fb8aa3b, v90
	v_exp_f32_e32 v90, v90
	s_nop 0
	v_mul_f32_e32 v86, v86, v90
	v_sub_f32_e32 v90, v106, v95
	v_mul_f32_e32 v90, 0x3fb8aa3b, v90
	v_exp_f32_e32 v90, v90
	s_waitcnt lgkmcnt(0)
	v_mul_f32_e32 v86, v200, v86
	v_cndmask_b32_e64 v86, v86, 0, s[66:67]
	v_mul_f32_e32 v87, v87, v90
	v_sub_f32_e32 v90, v106, v96
	v_mul_f32_e32 v90, 0x3fb8aa3b, v90
	v_exp_f32_e32 v90, v90
	v_mul_f32_e32 v87, v201, v87
	v_cndmask_b32_e64 v87, v87, 0, s[68:69]
	v_cvt_pk_bf16_f32 v86, v86, v87
	v_mul_f32_e32 v88, v88, v90
	v_sub_f32_e32 v90, v106, v97
	v_mul_f32_e32 v90, 0x3fb8aa3b, v90
	v_exp_f32_e32 v90, v90
	v_mul_f32_e32 v88, v202, v88
	v_cndmask_b32_e64 v88, v88, 0, s[70:71]
	v_mul_f32_e32 v89, v89, v90
	v_mul_f32_e32 v89, v203, v89
	v_cndmask_b32_e64 v89, v89, 0, s[72:73]
	v_cvt_pk_bf16_f32 v87, v88, v89
	v_mul_f32_e32 v88, 0x3fb8aa3b, v106
	v_exp_f32_e32 v92, v88
	ds_read_b128 v[88:91], v182
	ds_read_b128 v[94:97], v182 offset:4352
	ds_read_b128 v[98:101], v182 offset:8704
	ds_read_b128 v[102:105], v182 offset:13056
	s_waitcnt lgkmcnt(3)
	v_mfma_f32_16x16x32_bf16 v[88:91], v[88:91], v[80:83], 0
	s_waitcnt lgkmcnt(2)
	v_mfma_f32_16x16x32_bf16 v[94:97], v[94:97], v[80:83], 0
	s_waitcnt lgkmcnt(1)
	v_mfma_f32_16x16x32_bf16 v[98:101], v[98:101], v[80:83], 0
	s_waitcnt lgkmcnt(0)
	v_mfma_f32_16x16x32_bf16 v[80:83], v[102:105], v[80:83], 0
	ds_read_b128 v[102:105], v182 offset:64
	ds_read_b128 v[200:203], v182 offset:4416
	ds_read_b128 v[204:207], v182 offset:8768
	ds_read_b128 v[208:211], v182 offset:13120
	s_waitcnt lgkmcnt(3)
	v_mfma_f32_16x16x32_bf16 v[88:91], v[102:105], v[76:79], v[88:91]
	s_waitcnt lgkmcnt(2)
	v_mfma_f32_16x16x32_bf16 v[94:97], v[200:203], v[76:79], v[94:97]
	s_waitcnt lgkmcnt(1)
	v_mfma_f32_16x16x32_bf16 v[98:101], v[204:207], v[76:79], v[98:101]
	s_waitcnt lgkmcnt(0)
	v_mfma_f32_16x16x32_bf16 v[76:79], v[208:211], v[76:79], v[80:83]
	s_nop 2
	ds_read_b128 v[80:83], v182 offset:128
	ds_read_b128 v[102:105], v182 offset:4480
	ds_read_b128 v[200:203], v182 offset:8832
	ds_read_b128 v[204:207], v182 offset:13184
	s_waitcnt lgkmcnt(3)
	v_mfma_f32_16x16x32_bf16 v[80:83], v[80:83], v[72:75], v[88:91]
	s_waitcnt lgkmcnt(2)
	v_mfma_f32_16x16x32_bf16 v[88:91], v[102:105], v[72:75], v[94:97]
	s_waitcnt lgkmcnt(1)
	v_mfma_f32_16x16x32_bf16 v[94:97], v[200:203], v[72:75], v[98:101]
	s_waitcnt lgkmcnt(0)
	v_mfma_f32_16x16x32_bf16 v[72:75], v[204:207], v[72:75], v[76:79]
	s_nop 2
	ds_read_b128 v[76:79], v182 offset:192
	ds_read_b128 v[98:101], v182 offset:4544
	ds_read_b128 v[102:105], v182 offset:8896
	ds_read_b128 v[200:203], v182 offset:13248
	s_waitcnt lgkmcnt(3)
	v_mfma_f32_16x16x32_bf16 v[76:79], v[76:79], v[56:59], v[80:83]
	s_waitcnt lgkmcnt(2)
	v_mfma_f32_16x16x32_bf16 v[80:83], v[98:101], v[56:59], v[88:91]
	s_waitcnt lgkmcnt(1)
	v_mfma_f32_16x16x32_bf16 v[88:91], v[102:105], v[56:59], v[94:97]
	s_waitcnt lgkmcnt(0)
	v_mfma_f32_16x16x32_bf16 v[56:59], v[200:203], v[56:59], v[72:75]
	s_nop 2
	v_mul_f32_e64 v74, v92, v78
	v_mul_f32_e64 v75, v92, v79
	v_mul_f32_e32 v72, v92, v76
	v_mul_f32_e32 v73, v92, v77
	v_mul_f32_e32 v78, v92, v82
	v_mul_f32_e32 v79, v92, v83
	v_mul_f32_e32 v76, v92, v80
	v_mul_f32_e32 v77, v92, v81
	v_mul_f32_e32 v82, v92, v90
	v_mul_f32_e32 v83, v92, v91
	v_mul_f32_e32 v80, v92, v88
	v_mul_f32_e32 v81, v92, v89
	v_mul_f32_e32 v58, v92, v58
	v_mul_f32_e32 v59, v92, v59
	v_mul_f32_e32 v56, v92, v56
	v_mul_f32_e32 v57, v92, v57
	ds_read_b64_tr_b16 v[88:89], v183
	ds_read_b64_tr_b16 v[92:93], v183 offset:32
	ds_read_b64_tr_b16 v[90:91], v183 offset:2304
	ds_read_b64_tr_b16 v[94:95], v183 offset:2336
	ds_read_b64_tr_b16 v[96:97], v183 offset:64
	ds_read_b64_tr_b16 v[98:99], v183 offset:2368
	ds_read_b64_tr_b16 v[100:101], v183 offset:96
	ds_read_b64_tr_b16 v[102:103], v183 offset:2400
	s_waitcnt lgkmcnt(5)
	v_mfma_f32_16x16x32_bf16 v[72:75], v[88:91], v[68:71], v[72:75]
	s_waitcnt lgkmcnt(4)
	v_mfma_f32_16x16x32_bf16 v[76:79], v[92:95], v[68:71], v[76:79]
	s_waitcnt lgkmcnt(2)
	v_mfma_f32_16x16x32_bf16 v[80:83], v[96:99], v[68:71], v[80:83]
	s_waitcnt lgkmcnt(0)
	v_mfma_f32_16x16x32_bf16 v[56:59], v[100:103], v[68:71], v[56:59]
	ds_read_b64_tr_b16 v[68:69], v185
	ds_read_b64_tr_b16 v[88:89], v185 offset:32
	ds_read_b64_tr_b16 v[70:71], v185 offset:2304
	ds_read_b64_tr_b16 v[90:91], v185 offset:2336
	ds_read_b64_tr_b16 v[92:93], v185 offset:64
	ds_read_b64_tr_b16 v[94:95], v185 offset:2368
	ds_read_b64_tr_b16 v[96:97], v185 offset:96
	ds_read_b64_tr_b16 v[98:99], v185 offset:2400
	s_waitcnt lgkmcnt(5)
	v_mfma_f32_16x16x32_bf16 v[68:71], v[68:71], v[64:67], v[72:75]
	s_waitcnt lgkmcnt(4)
	v_mfma_f32_16x16x32_bf16 v[72:75], v[88:91], v[64:67], v[76:79]
	s_waitcnt lgkmcnt(2)
	v_mfma_f32_16x16x32_bf16 v[76:79], v[92:95], v[64:67], v[80:83]
	s_waitcnt lgkmcnt(0)
	v_mfma_f32_16x16x32_bf16 v[56:59], v[96:99], v[64:67], v[56:59]
	ds_read_b64_tr_b16 v[64:65], v186
	ds_read_b64_tr_b16 v[80:81], v186 offset:32
	ds_read_b64_tr_b16 v[66:67], v186 offset:2304
	ds_read_b64_tr_b16 v[82:83], v186 offset:2336
	ds_read_b64_tr_b16 v[88:89], v186 offset:64
	ds_read_b64_tr_b16 v[90:91], v186 offset:2368
	ds_read_b64_tr_b16 v[92:93], v186 offset:96
	ds_read_b64_tr_b16 v[94:95], v186 offset:2400
	s_waitcnt lgkmcnt(5)
	v_mfma_f32_16x16x32_bf16 v[64:67], v[64:67], v[60:63], v[68:71]
	s_waitcnt lgkmcnt(4)
	v_mfma_f32_16x16x32_bf16 v[68:71], v[80:83], v[60:63], v[72:75]
	s_waitcnt lgkmcnt(2)
	v_mfma_f32_16x16x32_bf16 v[72:75], v[88:91], v[60:63], v[76:79]
	s_waitcnt lgkmcnt(0)
; #define LAS __attribute__((address_space(3)))
; __device__ __forceinline__ float bflo(unsigned w) { return __uint_as_float(w << 16); }
; __device__ __forceinline__ float bfhi(unsigned w) { return __uint_as_float(w & 0xffff0000u); }
; __device__ __forceinline__ unsigned pk2(float lo, float hi) { unsigned r; asm("v_cvt_pk_bf16_f32 %0, %1, %2" : "=v"(r) : "v"(lo), "v"(hi)); return r; }
; __device__ __forceinline__ float siluf_(float x) { return x * __builtin_amdgcn_rcpf(1.0f + __expf(-x)); }
; __device__ __forceinline__ void ssd_prompt(const Params& p, LAS unsigned char* lds, int b, int h) {
;     ...
;             for (int pt = 0; pt < 4; ++pt) { x0[pt] = tr4(sX, XROW, 32 * kb + 4 * fq, 16 * pt, fr); x1[pt] = tr4(sX, XROW, 32 * kb + 16 + 4 * fq, 16 * pt, fr); }
; #pragma unroll
;             for (int pt = 0; pt < 4; ++pt) { u32x4 w; w.x = x0[pt].x; w.y = x0[pt].y; w.z = x1[pt].x; w.w = x1[pt].y;
;                 y[pt] = __builtin_amdgcn_mfma_f32_16x16x32_bf16(__builtin_bit_cast(bf16x8, w), gfrag[kb], y[pt], 0, 0, 0); }
;         }
;         float ssq = 0.f;
;         {
;             u32x2 xx[4];
; #pragma unroll
;             for (int pt = 0; pt < 4; ++pt) xx[pt] = *(const LAS u32x2*)(sX + trow * XROW + 16 * pt + 4 * fq);
; #pragma unroll
;             for (int pt = 0; pt < 4; ++pt) {
;                 const int pc = 16 * pt + 4 * fq;
;                 const float zf[4] = {bflo(rz[pt].x), bfhi(rz[pt].x), bflo(rz[pt].y), bfhi(rz[pt].y)};
;                 const float xf[4] = {bflo(xx[pt].x), bfhi(xx[pt].x), bflo(xx[pt].y), bfhi(xx[pt].y)};
;                 float yo[4];
; #pragma unroll
;                 for (int jj = 0; jj < 4; ++jj) { const float v = (y[pt][jj] + Dh * xf[jj]) * siluf_(zf[jj]); yo[jj] = v; ssq += v * v; }
;                 u32x2 w; w.x = pk2(yo[0], yo[1]); w.y = pk2(yo[2], yo[3]);
;                 *(u32x2*)(A2 + (size_t)grow * 4096 + h * 64 + pc) = w;
;             }
	v_mfma_f32_16x16x32_bf16 v[56:59], v[92:95], v[60:63], v[56:59]
	ds_read_b64_tr_b16 v[60:61], v187
	ds_read_b64_tr_b16 v[76:77], v187 offset:32
	ds_read_b64_tr_b16 v[62:63], v187 offset:2304
	ds_read_b64_tr_b16 v[78:79], v187 offset:2336
	ds_read_b64_tr_b16 v[80:81], v187 offset:64
	ds_read_b64_tr_b16 v[82:83], v187 offset:2368
	ds_read_b64_tr_b16 v[88:89], v187 offset:96
	ds_read_b64_tr_b16 v[90:91], v187 offset:2400
	s_waitcnt lgkmcnt(4)
	v_mfma_f32_16x16x32_bf16 v[68:71], v[76:79], v[84:87], v[68:71]
	s_waitcnt vmcnt(13)
	v_lshlrev_b32_e32 v78, 16, v148
	v_add_u32_e32 v76, s2, v177
	v_ashrrev_i32_e32 v77, 31, v76
	v_mfma_f32_16x16x32_bf16 v[92:95], v[60:63], v[84:87], v[64:67]
	s_waitcnt lgkmcnt(2)
	v_mfma_f32_16x16x32_bf16 v[64:67], v[80:83], v[84:87], v[72:75]
	v_mul_f32_e32 v82, 0xbfb8aa3b, v78
	v_exp_f32_e32 v82, v82
	s_nop 0
	ds_read2_b64 v[72:75], v188 offset1:4
	ds_read2_b64 v[60:63], v188 offset0:8 offset1:12
	s_waitcnt lgkmcnt(2)
	v_mfma_f32_16x16x32_bf16 v[56:59], v[88:91], v[84:87], v[56:59]
	v_lshlrev_b64 v[80:81], 13, v[76:77]
	v_add_f32_e32 v82, 1.0, v82
	v_rcp_f32_e32 v106, v82
	s_waitcnt lgkmcnt(1)
	v_lshlrev_b32_e32 v79, 16, v72
	v_lshlrev_b32_e32 v82, 16, v149
	v_lshlrev_b32_e32 v83, 16, v73
	v_mul_f32_e32 v78, v106, v78
	v_mul_f32_e32 v79, v107, v79
	v_and_b32_e32 v73, 0xffff0000, v73
	v_add_f32_e32 v79, v92, v79
	v_mul_f32_e32 v84, v78, v79
	v_and_b32_e32 v78, 0xffff0000, v148
	v_and_b32_e32 v79, 0xffff0000, v72
	v_mul_f32_e32 v72, 0xbfb8aa3b, v78
	v_exp_f32_e32 v72, v72
	s_nop 0
	v_add_f32_e32 v72, 1.0, v72
	v_rcp_f32_e32 v106, v72
	s_nop 0
	v_mul_f32_e32 v78, v106, v78
	v_mul_f32_e32 v79, v107, v79
	s_nop 0
	v_add_f32_e32 v72, v93, v79
	v_mul_f32_e32 v79, v78, v72
	v_mul_f32_e32 v72, 0xbfb8aa3b, v82
	v_exp_f32_e32 v72, v72
	v_mul_f32_e32 v78, v79, v79
	v_fmac_f32_e32 v78, v84, v84
	v_add_f32_e32 v72, 1.0, v72
	v_rcp_f32_e32 v106, v72
	s_nop 0
	v_mul_f32_e32 v82, v106, v82
	v_mul_f32_e32 v83, v107, v83
	s_nop 0
	v_add_f32_e32 v72, v94, v83
	v_mul_f32_e32 v83, v82, v72
	v_and_b32_e32 v72, 0xffff0000, v149
	v_mul_f32_e32 v82, 0xbfb8aa3b, v72
	v_exp_f32_e32 v82, v82
	v_fmac_f32_e32 v78, v83, v83
	v_add_f32_e32 v82, 1.0, v82
	v_rcp_f32_e32 v106, v82
	v_cvt_pk_bf16_f32 v82, v84, v79
	s_nop 0
	v_mul_f32_e32 v72, v106, v72
	v_mul_f32_e32 v73, v107, v73
	s_nop 0
	v_add_f32_e32 v73, v95, v73
	v_mul_f32_e32 v72, v72, v73
	v_fmac_f32_e32 v78, v72, v72
	v_cvt_pk_bf16_f32 v83, v83, v72
	v_lshl_add_u64 v[72:73], v[142:143], 0, v[80:81]
	s_waitcnt vmcnt(12)
	v_lshlrev_b32_e32 v80, 16, v146
	v_mul_f32_e32 v79, 0xbfb8aa3b, v80
	v_exp_f32_e32 v79, v79
	v_lshlrev_b32_e32 v81, 16, v74
	global_store_dwordx2 v[72:73], v[82:83], off
	v_add_f32_e32 v79, 1.0, v79
	v_rcp_f32_e32 v106, v79
	s_nop 0
	v_mul_f32_e32 v80, v106, v80
	v_mul_f32_e32 v81, v107, v81
	s_nop 0
	v_add_f32_e32 v68, v68, v81
	v_mul_f32_e32 v79, v80, v68
	v_and_b32_e32 v80, 0xffff0000, v146
	v_mul_f32_e32 v68, 0xbfb8aa3b, v80
	v_exp_f32_e32 v68, v68
	v_and_b32_e32 v81, 0xffff0000, v74
	v_fmac_f32_e32 v78, v79, v79
	v_add_f32_e32 v68, 1.0, v68
	v_rcp_f32_e32 v106, v68
	s_nop 0
	v_mul_f32_e32 v80, v106, v80
	v_mul_f32_e32 v81, v107, v81
	s_nop 0
	v_add_f32_e32 v68, v69, v81
	v_mul_f32_e32 v74, v80, v68
	v_lshlrev_b32_e32 v68, 16, v147
	v_mul_f32_e32 v80, 0xbfb8aa3b, v68
	v_exp_f32_e32 v80, v80
	v_lshlrev_b32_e32 v69, 16, v75
	v_fmac_f32_e32 v78, v74, v74
	v_add_f32_e32 v80, 1.0, v80
	v_rcp_f32_e32 v106, v80
	s_nop 0
	v_mul_f32_e32 v68, v106, v68
	v_mul_f32_e32 v69, v107, v69
	s_nop 0
	v_add_f32_e32 v69, v70, v69
	v_mul_f32_e32 v70, v68, v69
	v_and_b32_e32 v68, 0xffff0000, v147
	v_and_b32_e32 v69, 0xffff0000, v75
	v_mul_f32_e32 v75, 0xbfb8aa3b, v68
	v_exp_f32_e32 v75, v75
	v_fmac_f32_e32 v78, v70, v70
	v_add_f32_e32 v75, 1.0, v75
	v_rcp_f32_e32 v106, v75
	s_nop 0
	v_mul_f32_e32 v68, v106, v68
	v_mul_f32_e32 v69, v107, v69
	s_nop 0
	v_add_f32_e32 v69, v71, v69
	v_mul_f32_e32 v69, v68, v69
	v_cvt_pk_bf16_f32 v68, v79, v74
	v_fmac_f32_e32 v78, v69, v69
	v_cvt_pk_bf16_f32 v69, v70, v69
	global_store_dwordx2 v[72:73], v[68:69], off offset:32
	s_waitcnt vmcnt(13)
; __device__ __forceinline__ float bflo(unsigned w) { return __uint_as_float(w << 16); }
; __device__ __forceinline__ float bfhi(unsigned w) { return __uint_as_float(w & 0xffff0000u); }
; __device__ __forceinline__ unsigned pk2(float lo, float hi) { unsigned r; asm("v_cvt_pk_bf16_f32 %0, %1, %2" : "=v"(r) : "v"(lo), "v"(hi)); return r; }
; __device__ __forceinline__ float siluf_(float x) { return x * __builtin_amdgcn_rcpf(1.0f + __expf(-x)); }
; __device__ __forceinline__ void ssd_prompt(const Params& p, LAS unsigned char* lds, int b, int h) {
;     ...
;             for (int pt = 0; pt < 4; ++pt) {
;                 const int pc = 16 * pt + 4 * fq;
;                 const float zf[4] = {bflo(rz[pt].x), bfhi(rz[pt].x), bflo(rz[pt].y), bfhi(rz[pt].y)};
;                 const float xf[4] = {bflo(xx[pt].x), bfhi(xx[pt].x), bflo(xx[pt].y), bfhi(xx[pt].y)};
;                 float yo[4];
; #pragma unroll
;                 for (int jj = 0; jj < 4; ++jj) { const float v = (y[pt][jj] + Dh * xf[jj]) * siluf_(zf[jj]); yo[jj] = v; ssq += v * v; }
;                 u32x2 w; w.x = pk2(yo[0], yo[1]); w.y = pk2(yo[2], yo[3]);
;                 *(u32x2*)(A2 + (size_t)grow * 4096 + h * 64 + pc) = w;
;             }
;         }
;         ssq += __shfl_xor(ssq, 16); ssq += __shfl_xor(ssq, 32);
;         if (fq == 0) YSS[(size_t)grow * 32 + h] = ssq;
	v_lshlrev_b32_e32 v68, 16, v144
	v_mul_f32_e32 v70, 0xbfb8aa3b, v68
	v_exp_f32_e32 v70, v70
	s_waitcnt lgkmcnt(0)
	v_lshlrev_b32_e32 v69, 16, v60
	v_add_f32_e32 v70, 1.0, v70
	v_rcp_f32_e32 v106, v70
	s_nop 0
	v_mul_f32_e32 v68, v106, v68
	v_mul_f32_e32 v69, v107, v69
	s_nop 0
	v_add_f32_e32 v64, v64, v69
	v_mul_f32_e32 v70, v68, v64
	v_and_b32_e32 v68, 0xffff0000, v144
	v_and_b32_e32 v69, 0xffff0000, v60
	v_mul_f32_e32 v60, 0xbfb8aa3b, v68
	v_exp_f32_e32 v60, v60
	v_lshlrev_b32_e32 v64, 16, v145
	v_fmac_f32_e32 v78, v70, v70
	v_add_f32_e32 v60, 1.0, v60
	v_rcp_f32_e32 v106, v60
	s_nop 0
	v_mul_f32_e32 v68, v106, v68
	v_mul_f32_e32 v69, v107, v69
	s_nop 0
	v_add_f32_e32 v60, v65, v69
	v_mul_f32_e32 v68, v68, v60
	v_mul_f32_e32 v60, 0xbfb8aa3b, v64
	v_exp_f32_e32 v60, v60
	v_lshlrev_b32_e32 v65, 16, v61
	v_and_b32_e32 v61, 0xffff0000, v61
	v_fmac_f32_e32 v78, v68, v68
	v_add_f32_e32 v60, 1.0, v60
	v_rcp_f32_e32 v106, v60
	s_nop 0
	v_mul_f32_e32 v64, v106, v64
	v_mul_f32_e32 v65, v107, v65
	s_nop 0
	v_add_f32_e32 v60, v66, v65
	v_mul_f32_e32 v64, v64, v60
	v_and_b32_e32 v60, 0xffff0000, v145
	v_mul_f32_e32 v65, 0xbfb8aa3b, v60
	v_exp_f32_e32 v65, v65
	v_fmac_f32_e32 v78, v64, v64
	v_add_f32_e32 v65, 1.0, v65
	v_rcp_f32_e32 v106, v65
	s_nop 0
	v_mul_f32_e32 v60, v106, v60
	v_mul_f32_e32 v61, v107, v61
	s_nop 0
	v_add_f32_e32 v61, v67, v61
	v_mul_f32_e32 v61, v60, v61
	v_cvt_pk_bf16_f32 v60, v70, v68
	v_fmac_f32_e32 v78, v61, v61
	v_cvt_pk_bf16_f32 v61, v64, v61
	global_store_dwordx2 v[72:73], v[60:61], off offset:64
	s_waitcnt vmcnt(13)
	v_lshlrev_b32_e32 v60, 16, v140
	v_mul_f32_e32 v64, 0xbfb8aa3b, v60
	v_exp_f32_e32 v64, v64
	v_lshlrev_b32_e32 v61, 16, v62
	v_add_f32_e32 v64, 1.0, v64
	v_rcp_f32_e32 v106, v64
	s_nop 0
	v_mul_f32_e32 v60, v106, v60
	v_mul_f32_e32 v61, v107, v61
	s_nop 0
	v_add_f32_e32 v56, v56, v61
	v_mul_f32_e32 v64, v60, v56
	v_and_b32_e32 v60, 0xffff0000, v140
	v_mul_f32_e32 v56, 0xbfb8aa3b, v60
	v_exp_f32_e32 v56, v56
	v_and_b32_e32 v61, 0xffff0000, v62
	v_fmac_f32_e32 v78, v64, v64
	v_add_f32_e32 v56, 1.0, v56
	v_rcp_f32_e32 v106, v56
	s_nop 0
	v_mul_f32_e32 v60, v106, v60
	v_mul_f32_e32 v61, v107, v61
	s_nop 0
	v_add_f32_e32 v56, v57, v61
	v_mul_f32_e32 v60, v60, v56
	v_lshlrev_b32_e32 v56, 16, v141
	v_mul_f32_e32 v61, 0xbfb8aa3b, v56
	v_exp_f32_e32 v61, v61
	v_lshlrev_b32_e32 v57, 16, v63
	v_fmac_f32_e32 v78, v60, v60
	v_add_f32_e32 v61, 1.0, v61
	v_rcp_f32_e32 v106, v61
	s_nop 0
	v_mul_f32_e32 v56, v106, v56
	v_mul_f32_e32 v57, v107, v57
	s_nop 0
	v_add_f32_e32 v57, v58, v57
	v_mul_f32_e32 v58, v56, v57
	v_and_b32_e32 v56, 0xffff0000, v141
	v_mul_f32_e32 v61, 0xbfb8aa3b, v56
	v_exp_f32_e32 v61, v61
	v_and_b32_e32 v57, 0xffff0000, v63
	v_fmac_f32_e32 v78, v58, v58
	v_add_f32_e32 v61, 1.0, v61
	v_rcp_f32_e32 v106, v61
	s_nop 0
	v_mul_f32_e32 v56, v106, v56
	v_mul_f32_e32 v57, v107, v57
	s_nop 0
	v_add_f32_e32 v57, v59, v57
	v_mul_f32_e32 v57, v56, v57
	v_fmac_f32_e32 v78, v57, v57
	v_cvt_pk_bf16_f32 v57, v58, v57
	v_cvt_pk_bf16_f32 v56, v64, v60
	global_store_dwordx2 v[72:73], v[56:57], off offset:96
	v_and_b32_e32 v57, 64, v189
	v_xor_b32_e32 v56, 16, v189
	v_add_u32_e32 v57, 64, v57
	v_cmp_lt_i32_e32 vcc, v56, v57
	v_xor_b32_e32 v58, 32, v189
	s_nop 0
	v_cndmask_b32_e32 v56, v189, v56, vcc
	v_lshlrev_b32_e32 v56, 2, v56
	ds_bpermute_b32 v56, v56, v78
	v_cmp_lt_i32_e32 vcc, v58, v57
	s_waitcnt lgkmcnt(0)
	v_add_f32_e32 v56, v78, v56
	v_cndmask_b32_e32 v57, v189, v58, vcc
	v_lshlrev_b32_e32 v57, 2, v57
	ds_bpermute_b32 v57, v57, v56
	s_mov_b64 s[2:3], exec
	v_readlane_b32 s74, v244, 63
	v_readlane_b32 s75, v243, 0
	s_and_b64 s[74:75], s[2:3], s[74:75]
	s_mov_b64 exec, s[74:75]
	s_cbranch_execz .LBB0_529
	v_lshlrev_b64 v[58:59], 7, v[76:77]
	v_lshl_add_u64 v[58:59], s[18:19], 0, v[58:59]
	s_waitcnt lgkmcnt(0)
	v_add_f32_e32 v56, v56, v57
	global_store_dword v[58:59], v56, off
	s_branch .LBB0_529
